# stack6 + cached K/V f32->bf16 conversion moved from P0 to the P2 tail of workgroups 128..255 (they finish ~10us early)
# speedup vs baseline: 1.0058x; 1.0058x over previous
.LBB0_100:
	s_or_b64 exec, exec, s[4:5]
	s_mov_b32 s0, 0x40000
	s_mov_b64 s[4:5], s[90:91]
	s_mov_b64 s[12:13], s[90:91]
	s_mov_b64 vcc, 0
	s_and_saveexec_b64 s[8:9], vcc
	s_cbranch_execz .LBB0_105
	s_load_dwordx2 s[10:11], s[4:5], 0x18
	s_nop 0
	s_load_dwordx2 s[12:13], s[12:13], 0x20
	v_lshlrev_b32_e32 v3, 3, v0
	s_load_dword s0, s[90:91], 0xe0
	v_lshl_or_b32 v3, s92, 12, v3
	s_mov_b64 s[40:41], 0
	s_mov_b32 s1, 0x20000
	s_mov_b32 s2, 0x1ffff
	s_waitcnt lgkmcnt(0)
	s_lshl_b32 s0, s0, 12
	s_mov_b32 s3, 0x3ffff
	s_branch .LBB0_103

.LBB0_464:
	s_load_dwordx2 s[98:99], s[90:91], 0x18
	s_load_dwordx2 s[100:101], s[90:91], 0x20
	v_lshl_or_b32 v2, s92, 9, v0
	v_add_u32_e32 v2, 0xffff0000, v2
	v_lshlrev_b32_e32 v3, 3, v2
	v_add_u32_e32 v4, 0x80000, v3
	v_and_b32_e32 v5, 0xffffffc0, v3
	v_lshrrev_b32_e32 v12, 1, v3
	v_and_or_b32 v5, v12, 28, v5
	v_or_b32_e32 v6, 32, v5
	v_lshlrev_b32_e32 v5, 2, v5
	v_lshlrev_b32_e32 v6, 2, v6
	v_and_b32_e32 v7, 0xffffffc0, v4
	v_lshrrev_b32_e32 v13, 1, v4
	v_and_or_b32 v7, v13, 28, v7
	v_or_b32_e32 v8, 32, v7
	v_lshlrev_b32_e32 v7, 2, v7
	v_lshlrev_b32_e32 v8, 2, v8
	v_lshlrev_b32_e32 v9, 2, v3
	v_lshlrev_b32_e32 v10, 2, v4
	s_waitcnt lgkmcnt(0)
	global_load_dwordx4 v[20:23], v5, s[98:99] nt
	global_load_dwordx4 v[24:27], v6, s[98:99] nt
	global_load_dwordx4 v[28:31], v7, s[98:99] nt
	global_load_dwordx4 v[32:35], v8, s[98:99] nt
	global_load_dwordx4 v[36:39], v9, s[100:101] nt
	global_load_dwordx4 v[40:43], v9, s[100:101] offset:16 nt
	global_load_dwordx4 v[44:47], v10, s[100:101] nt
	global_load_dwordx4 v[48:51], v10, s[100:101] offset:16 nt
	v_lshrrev_b32_e32 v14, 18, v3
	v_mul_u32_u24_e32 v14, 0x180000, v14
	v_and_b32_e32 v16, 0x3ffff, v3
	v_lshl_add_u32 v14, v16, 1, v14
	v_lshrrev_b32_e32 v15, 18, v4
	v_mul_u32_u24_e32 v15, 0x180000, v15
	v_and_b32_e32 v16, 0x3ffff, v4
	v_lshl_add_u32 v15, v16, 1, v15
	v_add_u32_e32 v16, 0x8800000, v14
	v_add_u32_e32 v17, 0x8800000, v15
	v_add_u32_e32 v18, 0x8e00000, v14
	v_add_u32_e32 v19, 0x8e00000, v15
	s_waitcnt vmcnt(6)
	v_cvt_pk_bf16_f32 v20, v20, v21
	v_cvt_pk_bf16_f32 v21, v22, v23
	v_cvt_pk_bf16_f32 v22, v24, v25
	v_cvt_pk_bf16_f32 v23, v26, v27
	global_store_dwordx4 v16, v[20:23], s[18:19]
	s_waitcnt vmcnt(5)
	v_cvt_pk_bf16_f32 v28, v28, v29
	v_cvt_pk_bf16_f32 v29, v30, v31
	v_cvt_pk_bf16_f32 v30, v32, v33
	v_cvt_pk_bf16_f32 v31, v34, v35
	global_store_dwordx4 v17, v[28:31], s[18:19]
	s_waitcnt vmcnt(4)
	v_cvt_pk_bf16_f32 v36, v36, v37
	v_cvt_pk_bf16_f32 v37, v38, v39
	v_cvt_pk_bf16_f32 v38, v40, v41
	v_cvt_pk_bf16_f32 v39, v42, v43
	global_store_dwordx4 v18, v[36:39], s[18:19]
	s_waitcnt vmcnt(3)
	v_cvt_pk_bf16_f32 v44, v44, v45
	v_cvt_pk_bf16_f32 v45, v46, v47
	v_cvt_pk_bf16_f32 v46, v48, v49
	v_cvt_pk_bf16_f32 v47, v50, v51
	global_store_dwordx4 v19, v[44:47], s[18:19]
	v_readlane_b32 s23, v255, 7
